# attention P.V hoist (two MFMAs per step into the pack tail): counted lgkmcnt(11) in front of them instead of lgkmcnt(0)
# baseline (speedup 1.0000x reference)
.LBB0_1004:
	v_mfma_f32_32x32x16_bf16 v[68:83], v[246:249], v[250:253], 0
	v_mfma_f32_32x32x16_bf16 v[68:83], v[136:139], v[100:103], v[68:83]
	v_add_u32_e32 v2, s45, v189
	ds_read_b128 v[184:187], v2 offset:96
	ds_read_b128 v[210:213], v2 offset:128
	ds_read_b128 v[214:217], v2 offset:6752
	ds_read_b128 v[218:221], v2 offset:160
	ds_read_b128 v[222:225], v2 offset:6784
	ds_read_b128 v[226:229], v2 offset:6816
	v_add_u32_e32 v2, s39, v200
	ds_read_b128 v[176:179], v2 offset:53248
	ds_read_b128 v[164:167], v2 offset:53280
	ds_read_b128 v[230:233], v2 offset:57856
	ds_read_b128 v[238:241], v2 offset:57888
	ds_read_b128 v[160:163], v2 offset:53312
	ds_read_b128 v[156:159], v2 offset:53344
	ds_read_b128 v[242:245], v2 offset:57920
	ds_read_b128 v[152:155], v2 offset:57952
	v_mfma_f32_32x32x16_bf16 v[84:99], v[246:249], v[250:253], 0
	v_mfma_f32_32x32x16_bf16 v[84:99], v[132:135], v[100:103], v[84:99]
	v_exp_f32_e32 v52, v52
	v_exp_f32_e32 v183, v36
	v_exp_f32_e32 v132, v53
	v_exp_f32_e32 v53, v54
	v_mfma_f32_32x32x16_bf16 v[68:83], v[144:147], v[104:107], v[68:83]
	v_exp_f32_e32 v54, v38
	v_exp_f32_e32 v36, v55
	v_exp_f32_e32 v55, v56
	v_exp_f32_e32 v56, v40
	v_mfma_f32_32x32x16_bf16 v[84:99], v[128:131], v[104:107], v[84:99]
	v_exp_f32_e32 v40, v39
	v_exp_f32_e32 v38, v57
	v_exp_f32_e32 v57, v58
	v_exp_f32_e32 v58, v41
	v_mfma_f32_32x32x16_bf16 v[68:83], v[140:143], v[108:111], v[68:83]
	v_add_u32_e32 v181, s44, v189
	ds_read_b128 v[144:147], v181
	ds_read_b128 v[172:175], v181 offset:32
	ds_read_b128 v[136:139], v181 offset:6656
	ds_read_b128 v[168:171], v181 offset:64
	ds_read_b128 v[148:151], v181 offset:6688
	ds_read_b128 v[140:143], v181 offset:6720
	v_exp_f32_e32 v2, v37
	v_mfma_f32_32x32x16_bf16 v[84:99], v[124:127], v[108:111], v[84:99]
	v_exp_f32_e32 v124, v59
	v_exp_f32_e32 v41, v60
	v_add_f32_e32 v133, v52, v183
	v_add_f32_e32 v37, v53, v54
	s_waitcnt lgkmcnt(14)
	v_mfma_f32_32x32x16_bf16 v[68:83], v[214:217], v[112:115], v[68:83]
	v_exp_f32_e32 v214, v42
	v_exp_f32_e32 v59, v44
	v_exp_f32_e32 v60, v43
	v_exp_f32_e32 v126, v61
	v_mfma_f32_32x32x16_bf16 v[84:99], v[184:187], v[112:115], v[84:99]
	v_exp_f32_e32 v61, v62
	v_exp_f32_e32 v62, v45
	v_exp_f32_e32 v128, v63
	v_exp_f32_e32 v63, v64
	v_mfma_f32_32x32x16_bf16 v[68:83], v[222:225], v[116:119], v[68:83]
	v_exp_f32_e32 v216, v48
	v_exp_f32_e32 v64, v47
	v_exp_f32_e32 v130, v65
	v_mfma_f32_32x32x16_bf16 v[84:99], v[210:213], v[116:119], v[84:99]
	v_exp_f32_e32 v65, v66
	v_exp_f32_e32 v215, v46
	v_exp_f32_e32 v185, v50
	v_mfma_f32_32x32x16_bf16 v[68:83], v[226:229], v[120:123], v[68:83]
	v_exp_f32_e32 v66, v49
	v_exp_f32_e32 v134, v67
	v_add_f32_e32 v39, v55, v56
	v_add_f32_e32 v125, v57, v214
	v_mfma_f32_32x32x16_bf16 v[84:99], v[218:221], v[120:123], v[84:99]
	v_add_f32_e32 v127, v41, v59
	v_add_f32_e32 v129, v61, v215
	v_add_f32_e32 v131, v63, v216
	v_add_f32_e32 v135, v65, v185
	v_exp_f32_e32 v184, v51
	v_cvt_pk_bf16_f32 v42, v52, v132
	v_cvt_pk_bf16_f32 v43, v53, v36
	v_cvt_pk_bf16_f32 v44, v55, v38
	v_cvt_pk_bf16_f32 v45, v57, v124
	v_cvt_pk_bf16_f32 v46, v41, v126
	v_cvt_pk_bf16_f32 v47, v61, v128
	s_waitcnt lgkmcnt(11)
	v_mfma_f32_32x32x16_bf16 v[4:19], v[42:45], v[230:233], v[4:19]
	v_cvt_pk_bf16_f32 v48, v63, v130
	v_cvt_pk_bf16_f32 v49, v65, v134
	v_cvt_pk_bf16_f32 v50, v183, v2
	v_cvt_pk_bf16_f32 v51, v54, v40
	v_cvt_pk_bf16_f32 v52, v56, v58
	v_cvt_pk_bf16_f32 v53, v214, v60
	v_mfma_f32_32x32x16_bf16 v[20:35], v[42:45], v[176:179], v[20:35]
	v_cvt_pk_bf16_f32 v54, v59, v62
	v_cvt_pk_bf16_f32 v55, v215, v64
	v_cvt_pk_bf16_f32 v56, v216, v66
	v_cvt_pk_bf16_f32 v57, v185, v184
	s_add_i32 s14, s46, 5
	s_min_u32 s14, s14, s37
	s_add_i32 s15, s46, 3
	s_min_u32 s46, s15, s37
	s_mulk_i32 s14, 0x3000
	s_add_u32 s14, s10, s14
	s_addc_u32 s15, s11, 0
	s_lshl_b32 s46, s46, 13
	s_add_u32 s46, s12, s46
	s_addc_u32 s47, s13, 0
	s_add_i32 m0, s22, s45
	s_and_b64 s[48:49], s[4:5], exec
	s_waitcnt vmcnt(3) lgkmcnt(0)
	s_barrier
	v_mfma_f32_32x32x16_bf16 v[4:19], v[46:49], v[238:241], v[4:19]
	v_lshl_add_u64 v[186:187], s[14:15], 0, v[190:191]
	s_cselect_b32 s15, s15, s47
	s_cselect_b32 s14, s14, s46
	global_load_lds_dwordx4 v[186:187], off
	v_lshl_add_u64 v[186:187], s[14:15], 0, v[192:193]
	s_cselect_b32 s14, s45, s39
	s_add_i32 m0, s21, s14
	s_add_i32 s14, s23, s39
	global_load_lds_dwordx4 v[186:187], off
	v_lshl_add_u64 v[186:187], s[46:47], 0, v[194:195]
	s_add_i32 m0, s14, 0xd000
	s_nop 0
	global_load_lds_dwordx4 v[186:187], off
	v_max3_f32 v41, v84, v68, v85
	v_max3_f32 v59, v92, v76, v93
	v_add_f32_e32 v132, v132, v2
	v_max3_f32 v41, v41, v69, v86
	v_max3_f32 v59, v59, v77, v94
	v_mfma_f32_32x32x16_bf16 v[20:35], v[46:49], v[164:167], v[20:35]
	s_nop 0
	v_max3_f32 v41, v41, v70, v87
	v_max3_f32 v41, v41, v71, v88
	v_max3_f32 v59, v59, v78, v95
	v_max3_f32 v41, v41, v72, v89
	v_max3_f32 v59, v59, v79, v96
	s_nop 0
	v_max3_f32 v41, v41, v73, v90
	v_max3_f32 v183, v41, v74, v91
	v_mfma_f32_32x32x16_bf16 v[4:19], v[50:53], v[242:245], v[4:19]
	v_add_f32_e32 v41, v132, v133
	v_max3_f32 v59, v59, v80, v97
	v_add_f32_e64 v36, v36, v40
	v_add_f32_e64 v37, v37, v41
	v_max3_f32 v59, v59, v81, v98
	v_max3_f32 v186, v59, v82, v99
	v_add_f32_e32 v59, v36, v37
	v_add_f32_e32 v36, v38, v58
	v_add_f32_e32 v37, v39, v59
	v_mfma_f32_32x32x16_bf16 v[20:35], v[50:53], v[160:163], v[20:35]
	v_add_f32_e32 v61, v36, v37
	v_add_f32_e32 v36, v124, v60
	v_add_f32_e32 v37, v125, v61
	v_add_f32_e32 v63, v36, v37
	v_add_f32_e32 v36, v126, v62
	v_add_f32_e32 v37, v127, v63
	v_add_f32_e32 v65, v36, v37
	v_add_f32_e32 v36, v128, v64
	v_add_f32_e32 v37, v129, v65
	v_mfma_f32_32x32x16_bf16 v[20:35], v[54:57], v[156:159], v[20:35]
	v_add_f32_e32 v67, v36, v37
	v_add_f32_e32 v36, v130, v66
	v_add_f32_e32 v37, v131, v67
	v_add_f32_e32 v185, v36, v37
	v_add_f32_e32 v36, v134, v184
	v_add_f32_e32 v37, v135, v185
	v_add_f32_e32 v2, v36, v37
	v_max3_f32 v36, v183, v75, v186
	v_add_f32_e32 v2, v209, v2
	v_mfma_f32_32x32x16_bf16 v[4:19], v[54:57], v[152:155], v[4:19]
	v_max3_f32 v36, v36, v83, v36
	s_nop 0
	v_mov_b32_e32 v37, v36
	v_mov_b32_e32 v38, v36
	s_nop 0
	v_permlane32_swap_b32_e32 v37, v38
	v_max3_f32 v36, v37, v38, v36
	s_nop 0
	v_cmp_lt_f32_e32 vcc, s56, v36
	s_cbranch_vccz .LBB0_1008
	s_nop 0
	v_add_f32_e32 v210, v180, v36
	v_cvt_pk_bf16_f32 v210, v210, v210
	v_lshlrev_b32_e32 v210, 16, v210
	v_cndmask_b32_e32 v210, v180, v210, vcc
	v_sub_f32_e32 v36, v180, v210
	v_sub_f32_e32 v186, v210, v180
	v_xor_b32_e32 v250, 0x80000000, v210
	v_min_f32_e32 v36, 0, v36
	v_lshrrev_b32_e32 v250, 16, v250
	v_exp_f32_e32 v36, v36
	v_cndmask_b32_e64 v250, 0, v250, s[2:3]
	s_and_saveexec_b64 s[14:15], s[2:3]
	ds_write_b32 v202, v36
	s_or_b64 exec, exec, s[14:15]
	v_mul_f32_e32 v2, v2, v36
	ds_read_b32 v36, v1
	ds_read_b32 v37, v1 offset:4
	ds_read_b32 v38, v1 offset:8
	ds_read_b32 v39, v1 offset:12
	ds_read_b32 v40, v1 offset:32
	ds_read_b32 v41, v1 offset:36
	ds_read_b32 v42, v1 offset:40
	ds_read_b32 v43, v1 offset:44
	ds_read_b32 v44, v1 offset:64
	ds_read_b32 v45, v1 offset:68
	ds_read_b32 v46, v1 offset:72
	ds_read_b32 v47, v1 offset:76
	ds_read_b32 v48, v1 offset:96
	ds_read_b32 v49, v1 offset:100
	ds_read_b32 v50, v1 offset:104
	ds_read_b32 v51, v1 offset:108
	s_waitcnt lgkmcnt(0)
	v_pk_mul_f32 v[20:21], v[20:21], v[36:37]
	v_pk_mul_f32 v[22:23], v[22:23], v[38:39]
	v_pk_mul_f32 v[24:25], v[24:25], v[40:41]
	v_pk_mul_f32 v[26:27], v[26:27], v[42:43]
	v_pk_mul_f32 v[28:29], v[28:29], v[44:45]
	v_pk_mul_f32 v[30:31], v[30:31], v[46:47]
	v_pk_mul_f32 v[32:33], v[32:33], v[48:49]
	v_pk_mul_f32 v[34:35], v[34:35], v[50:51]
	v_pk_mul_f32 v[4:5], v[4:5], v[36:37]
	v_pk_mul_f32 v[6:7], v[6:7], v[38:39]
	v_pk_mul_f32 v[8:9], v[8:9], v[40:41]
	v_pk_mul_f32 v[10:11], v[10:11], v[42:43]
	v_pk_mul_f32 v[12:13], v[12:13], v[44:45]
	v_pk_mul_f32 v[14:15], v[14:15], v[46:47]
	v_pk_mul_f32 v[16:17], v[16:17], v[48:49]
	v_pk_mul_f32 v[18:19], v[18:19], v[50:51]
	v_sub_f32_e32 v68, v68, v186
	v_sub_f32_e32 v69, v69, v186
	v_sub_f32_e32 v70, v70, v186
	v_sub_f32_e32 v71, v71, v186
	v_sub_f32_e32 v72, v72, v186
	v_sub_f32_e32 v73, v73, v186
	v_sub_f32_e32 v74, v74, v186
	v_sub_f32_e32 v75, v75, v186
	v_sub_f32_e32 v76, v76, v186
	v_sub_f32_e32 v77, v77, v186
	v_sub_f32_e32 v78, v78, v186
	v_sub_f32_e32 v79, v79, v186
	v_sub_f32_e32 v80, v80, v186
	v_sub_f32_e32 v81, v81, v186
	v_sub_f32_e32 v82, v82, v186
	v_sub_f32_e32 v83, v83, v186
	v_sub_f32_e32 v84, v84, v186
	v_sub_f32_e32 v85, v85, v186
	v_sub_f32_e32 v86, v86, v186
	v_sub_f32_e32 v87, v87, v186
	v_sub_f32_e32 v88, v88, v186
	v_sub_f32_e32 v89, v89, v186
	v_sub_f32_e32 v90, v90, v186
	v_sub_f32_e32 v91, v91, v186
	v_sub_f32_e32 v92, v92, v186
	v_sub_f32_e32 v93, v93, v186
	v_sub_f32_e32 v94, v94, v186
	v_sub_f32_e32 v95, v95, v186
	v_sub_f32_e32 v96, v96, v186
	v_sub_f32_e32 v97, v97, v186
	v_sub_f32_e32 v98, v98, v186
	v_sub_f32_e32 v99, v99, v186
	s_mov_b32 s56, 0x41000000
	s_branch .LBB0_1009

; __device__ __forceinline__ void ph_attn(Frame& F) {
;     ...
;         for (int t = 0; t < NT; t += 2) {
;             AT_STEP(pA0, pA1, pB0, pB1, t);
;             AT_STEP(pB0, pB1, pA0, pA1, t + 1);
;         }
.LBB0_1009:
	v_mfma_f32_32x32x16_bf16 v[36:51], v[246:249], v[250:253], 0
	v_mfma_f32_32x32x16_bf16 v[36:51], v[136:139], v[100:103], v[36:51]
	v_add_u32_e32 v52, s43, v200
	ds_read_b128 v[212:215], v181 offset:96
	ds_read_b128 v[216:219], v181 offset:128
	ds_read_b128 v[220:223], v181 offset:6752
	ds_read_b128 v[224:227], v181 offset:160
	ds_read_b128 v[228:231], v181 offset:6784
	ds_read_b128 v[238:241], v181 offset:6816
	ds_read_b128 v[160:163], v52 offset:53248
	ds_read_b128 v[164:167], v52 offset:53280
	ds_read_b128 v[184:187], v52 offset:57856
	ds_read_b128 v[180:183], v52 offset:57888
	ds_read_b128 v[156:159], v52 offset:53312
	ds_read_b128 v[152:155], v52 offset:53344
	v_add_u32_e32 v209, s41, v189
	v_mfma_f32_32x32x16_bf16 v[36:51], v[148:151], v[104:107], v[36:51]
	ds_read_b128 v[176:179], v52 offset:57920
	ds_read_b128 v[148:151], v52 offset:57952
	v_exp_f32_e32 v211, v84
	v_exp_f32_e32 v232, v68
	v_exp_f32_e32 v233, v85
	v_mfma_f32_32x32x16_bf16 v[52:67], v[246:249], v[250:253], 0
	v_mfma_f32_32x32x16_bf16 v[52:67], v[144:147], v[100:103], v[52:67]
	v_exp_f32_e32 v235, v69
	v_add_f32_e32 v68, v211, v232
	v_add_f32_e32 v69, v233, v235
	v_add_f32_e32 v68, v69, v68
	v_mfma_f32_32x32x16_bf16 v[52:67], v[172:175], v[104:107], v[52:67]
	v_exp_f32_e32 v173, v70
	v_exp_f32_e32 v172, v86
	v_exp_f32_e32 v174, v87
	v_exp_f32_e32 v175, v71
	v_add_f32_e32 v69, v172, v173
	v_add_f32_e32 v68, v69, v68
	v_mfma_f32_32x32x16_bf16 v[52:67], v[168:171], v[108:111], v[52:67]
	v_add_f32_e32 v69, v174, v175
	v_add_f32_e32 v168, v69, v68
	v_exp_f32_e32 v71, v88
	v_exp_f32_e32 v85, v72
	v_exp_f32_e32 v70, v89
	v_exp_f32_e32 v84, v73
	v_exp_f32_e32 v73, v90
	v_exp_f32_e32 v87, v74
	v_exp_f32_e32 v72, v91
	v_exp_f32_e32 v86, v75
	v_pk_add_f32 v[68:69], v[70:71], v[84:85]
	v_mfma_f32_32x32x16_bf16 v[36:51], v[140:143], v[108:111], v[36:51]
	v_add_f32_e32 v69, v69, v168
	v_add_f32_e32 v74, v68, v69
	v_add_f32_e64 v68, v72, v86
	v_add_f32_e64 v69, v73, v87
	ds_read_b128 v[132:135], v209
	ds_read_b128 v[128:131], v209 offset:32
	ds_read_b128 v[136:139], v209 offset:6656
	ds_read_b128 v[124:127], v209 offset:64
	v_add_f32_e32 v69, v69, v74
	v_add_f32_e32 v168, v68, v69
	v_exp_f32_e32 v75, v92
	v_exp_f32_e32 v89, v76
	v_exp_f32_e32 v74, v93
	v_exp_f32_e32 v88, v77
	v_exp_f32_e32 v77, v94
	s_waitcnt lgkmcnt(12)
	v_mfma_f32_32x32x16_bf16 v[36:51], v[220:223], v[112:115], v[36:51]
	v_exp_f32_e32 v91, v78
	v_exp_f32_e32 v76, v95
	v_exp_f32_e32 v90, v79
	v_pk_add_f32 v[68:69], v[74:75], v[88:89]
	ds_read_b128 v[144:147], v209 offset:6688
	ds_read_b128 v[140:143], v209 offset:6720
	v_mfma_f32_32x32x16_bf16 v[52:67], v[212:215], v[112:115], v[52:67]
	v_add_f32_e32 v69, v69, v168
	v_add_f32_e32 v78, v68, v69
	v_add_f32_e64 v68, v76, v90
	v_add_f32_e64 v69, v77, v91
	v_add_f32_e32 v69, v69, v78
	v_add_f32_e32 v168, v68, v69
	v_mfma_f32_32x32x16_bf16 v[36:51], v[228:231], v[116:119], v[36:51]
	v_exp_f32_e32 v79, v96
	v_exp_f32_e32 v93, v80
	v_exp_f32_e32 v78, v97
	v_exp_f32_e32 v92, v81
	v_mfma_f32_32x32x16_bf16 v[52:67], v[216:219], v[116:119], v[52:67]
	v_exp_f32_e32 v95, v98
	v_exp_f32_e32 v97, v82
	v_exp_f32_e32 v94, v99
	v_mfma_f32_32x32x16_bf16 v[36:51], v[238:241], v[120:123], v[36:51]
	v_exp_f32_e32 v96, v83
	v_pk_add_f32 v[68:69], v[78:79], v[92:93]
	s_nop 0
	v_add_f32_e32 v69, v69, v168
	v_add_f32_e32 v80, v68, v69
	v_pk_add_f32 v[68:69], v[94:95], v[96:97]
	v_mfma_f32_32x32x16_bf16 v[52:67], v[224:227], v[120:123], v[52:67]
	v_add_f32_e32 v69, v69, v80
	v_add_f32_e32 v68, v68, v69
	v_add_f32_e32 v209, v2, v68
	v_cvt_pk_bf16_f32 v68, v211, v233
	v_cvt_pk_bf16_f32 v69, v172, v174
	v_cvt_pk_bf16_f32 v70, v71, v70
	v_cvt_pk_bf16_f32 v71, v73, v72
	v_cvt_pk_bf16_f32 v80, v75, v74
	v_cvt_pk_bf16_f32 v81, v77, v76
	s_waitcnt lgkmcnt(11)
	v_mfma_f32_32x32x16_bf16 v[4:19], v[68:71], v[184:187], v[4:19]
	v_cvt_pk_bf16_f32 v82, v79, v78
	v_cvt_pk_bf16_f32 v83, v95, v94
	v_cvt_pk_bf16_f32 v76, v232, v235
	v_cvt_pk_bf16_f32 v77, v173, v175
	v_cvt_pk_bf16_f32 v78, v85, v84
	v_cvt_pk_bf16_f32 v79, v87, v86
	v_mfma_f32_32x32x16_bf16 v[20:35], v[68:71], v[160:163], v[20:35]
	v_cvt_pk_bf16_f32 v72, v89, v88
	v_cvt_pk_bf16_f32 v73, v91, v90
	v_cvt_pk_bf16_f32 v74, v93, v92
	v_cvt_pk_bf16_f32 v75, v97, v96
	s_cmp_ge_u32 s42, s36
	s_cbranch_scc1 .Lattn_exit
	s_mov_b32 s14, s41
	s_mov_b32 s15, s38
	s_mov_b32 s41, s45
	s_mov_b32 s38, s44
	s_mov_b32 s44, s40
	s_mov_b32 s40, s43
	s_mov_b32 s46, s42
	s_add_i32 s42, s46, 4
	s_min_u32 s43, s42, s37
	s_add_i32 s42, s46, 2
	s_min_u32 s45, s42, s37
	s_mulk_i32 s43, 0x3000
	s_add_u32 s48, s10, s43
	s_addc_u32 s49, s11, 0
	s_lshl_b32 s43, s45, 13
	s_add_u32 s50, s12, s43
	s_addc_u32 s51, s13, 0
	s_add_i32 m0, s22, s38
	s_and_b64 s[52:53], s[4:5], exec
	s_waitcnt vmcnt(3) lgkmcnt(0)
	s_barrier
	s_branch .LBB0_999
